# SSD tile loop: next tile's first three B fragments read at the end of the current tile (no LDS wait before the first MFMA)
# baseline (speedup 1.0000x reference)
; __device__ __forceinline__ float ex2(float x) { return __builtin_amdgcn_exp2f(x); }
; #define LAS __attribute__((address_space(3)))
; __device__ __forceinline__ bf16x8 cat8(s16x4 lo, s16x4 hi) { return (bf16x8){lo[0], lo[1], lo[2], lo[3], hi[0], hi[1], hi[2], hi[3]}; }
; #define MFMA32(a, b, c) __builtin_amdgcn_mfma_f32_32x32x16_bf16((a), (b), (c), 0, 0, 0)
; __device__ __forceinline__ void ssd_stream(const Frame& F, const Args& A, int sidx) {
;     ...
;         const float acs_l = arr[lcol];
;         int r32o = r32; asm volatile("" : "+v"(r32o));
;         bf16x8 cf[8], af[8];
; #pragma unroll
;         for (int s = 0; s < 8; ++s) { cf[s] = *(LAS bf16x8*)(CT + lcol * BS_ + (16 * s + 8 * hh) * 2); af[s] = *(LAS bf16x8*)(ST + (32 * pt + r32) * BS_ + (16 * s + 8 * hh) * 2); }
;         __builtin_amdgcn_sched_barrier(0);
;         f32x16 Y;
; #pragma unroll
;         for (int i = 0; i < 16; ++i) Y[i] = 0.f;
; #pragma unroll
;         for (int s = 0; s < 8; ++s) Y = MFMA32(af[s], cf[s], Y);
;         { const float el = ex2(acs_l);
; #pragma unroll
;           for (int i = 0; i < 16; ++i) Y[i] *= el; }
; #pragma unroll 1
;         for (int sti = 0; sti <= lt; ++sti) {
;             {
;                 bf16x8 bfA[8]; f32x4 as4[4], dt4[4]; s16x4 xlo[2], xhi[2];
; #pragma unroll
;                 for (int s = 0; s < 8; ++s) bfA[s] = *(LAS bf16x8*)(BT + (32 * sti + r32) * BS_ + (16 * s + 8 * hh) * 2);
;     ...
;                 for (int s2 = 0; s2 < 2; ++s2) {
;                     const bf16x8 wf = packf8(Gt[8 * s2], Gt[8 * s2 + 1], Gt[8 * s2 + 2], Gt[8 * s2 + 3], Gt[8 * s2 + 4], Gt[8 * s2 + 5], Gt[8 * s2 + 6], Gt[8 * s2 + 7]);
;                     Y = MFMA32(cat8(xlo[s2], xhi[s2]), wf, Y);
;                 }
.LBB0_1304:
	v_lshl_add_u32 v18, v205, 2, s78
	v_mov_b32_e32 v34, v204
	v_add_u32_e32 v22, v206, v208
	s_waitcnt lgkmcnt(0)
	s_barrier
	ds_read_b32 v140, v18
	ds_read_b128 v[98:101], v225
	ds_read_b128 v[102:105], v225 offset:32
	ds_read_b128 v[18:21], v22
	ds_read_b128 v[36:39], v22 offset:32
	ds_read_b128 v[106:109], v225 offset:64
	ds_read_b128 v[110:113], v225 offset:96
	ds_read_b128 v[40:43], v22 offset:64
	ds_read_b128 v[44:47], v22 offset:96
	ds_read_b128 v[114:117], v225 offset:128
	ds_read_b128 v[118:121], v225 offset:160
	ds_read_b128 v[130:133], v22 offset:128
	ds_read_b128 v[134:137], v22 offset:160
	ds_read_b128 v[122:125], v225 offset:192
	ds_read_b128 v[126:129], v225 offset:224
	ds_read_b128 v[186:189], v22 offset:192
	ds_read_b128 v[190:193], v22 offset:224
	s_waitcnt lgkmcnt(13)
	v_mfma_f32_32x32x16_bf16 v[18:33], v[18:21], v[98:101], 0
	s_andn2_b64 vcc, exec, s[88:89]
	s_waitcnt lgkmcnt(12)
	v_mfma_f32_32x32x16_bf16 v[18:33], v[36:39], v[102:105], v[18:33]
	v_exp_f32_e32 v36, v140
	s_waitcnt lgkmcnt(9)
	v_mfma_f32_32x32x16_bf16 v[18:33], v[40:43], v[106:109], v[18:33]
	s_waitcnt lgkmcnt(8)
	v_mfma_f32_32x32x16_bf16 v[18:33], v[44:47], v[110:113], v[18:33]
	s_waitcnt lgkmcnt(5)
	v_mfma_f32_32x32x16_bf16 v[18:33], v[130:133], v[114:117], v[18:33]
	s_waitcnt lgkmcnt(4)
	v_mfma_f32_32x32x16_bf16 v[18:33], v[134:137], v[118:121], v[18:33]
	s_waitcnt lgkmcnt(1)
	v_mfma_f32_32x32x16_bf16 v[18:33], v[186:189], v[122:125], v[18:33]
	s_waitcnt lgkmcnt(0)
	v_mfma_f32_32x32x16_bf16 v[18:33], v[190:193], v[126:129], v[18:33]
	s_nop 11
	v_pk_mul_f32 v[18:19], v[36:37], v[18:19] op_sel_hi:[0,1]
	v_pk_mul_f32 v[32:33], v[36:37], v[32:33] op_sel_hi:[0,1]
	v_pk_mul_f32 v[30:31], v[36:37], v[30:31] op_sel_hi:[0,1]
	v_pk_mul_f32 v[28:29], v[36:37], v[28:29] op_sel_hi:[0,1]
	v_pk_mul_f32 v[26:27], v[36:37], v[26:27] op_sel_hi:[0,1]
	v_pk_mul_f32 v[24:25], v[36:37], v[24:25] op_sel_hi:[0,1]
	v_pk_mul_f32 v[22:23], v[36:37], v[22:23] op_sel_hi:[0,1]
	v_pk_mul_f32 v[20:21], v[36:37], v[20:21] op_sel_hi:[0,1]
	s_cbranch_vccnz .LBB0_1312
	v_cmp_gt_i32_e64 s[26:27], v150, v34
	v_cmp_lt_i32_e64 s[28:29], v150, v34
	v_cmp_gt_i32_e64 s[30:31], v1, v34
	v_cmp_gt_i32_e64 s[34:35], v162, v34
	v_cmp_gt_i32_e64 s[36:37], v151, v34
	v_cmp_gt_i32_e64 s[38:39], v164, v34
	v_cmp_gt_i32_e64 s[40:41], v163, v34
	v_cmp_gt_i32_e64 s[42:43], v166, v34
	v_cmp_gt_i32_e64 s[44:45], v165, v34
	v_cmp_gt_i32_e64 s[46:47], v168, v34
	v_cmp_gt_i32_e64 s[48:49], v167, v34
	v_cmp_gt_i32_e64 s[50:51], v170, v34
	v_cmp_gt_i32_e64 s[52:53], v169, v34
	v_cmp_gt_i32_e64 s[54:55], v172, v34
	v_cmp_gt_i32_e64 s[56:57], v171, v34
	v_cmp_gt_i32_e64 s[58:59], v174, v34
	v_add_u32_e32 v230, s66, v208
	s_add_i32 s68, s66, 0x1e47c
	s_mov_b32 s69, 0
	v_mov_b32_e32 v231, v222
	v_mov_b32_e32 v232, v221
	ds_read_b128 v[238:241], v232
	ds_read_b128 v[244:247], v232 offset:32
	ds_read_b128 v[248:251], v232 offset:64
	s_branch .LBB0_1307
.LBB0_1306:
	v_cvt_pk_bf16_f32 v34, v186, v187
	v_cvt_pk_bf16_f32 v35, v188, v189
	v_cvt_pk_bf16_f32 v36, v190, v191
	v_cvt_pk_bf16_f32 v37, v192, v193
	s_waitcnt lgkmcnt(2)
	s_nop 7
	v_mfma_f32_32x32x16_bf16 v[18:33], v[134:137], v[34:37], v[18:33]
	v_cvt_pk_bf16_f32 v34, v194, v195
	v_cvt_pk_bf16_f32 v35, v196, v197
	v_cvt_pk_bf16_f32 v36, v198, v199
	v_cvt_pk_bf16_f32 v37, v200, v201
	s_waitcnt lgkmcnt(0)
	v_mfma_f32_32x32x16_bf16 v[18:33], v[130:133], v[34:37], v[18:33]
	s_add_i32 s69, s69, 1
	s_addk_i32 s68, 0x80
	v_add_u32_e32 v230, 0x80, v230
	v_add_u32_e32 v232, 0x2200, v232
	ds_read_b128 v[238:241], v232
	ds_read_b128 v[244:247], v232 offset:32
	ds_read_b128 v[248:251], v232 offset:64
	s_cmp_eq_u32 s63, s69
	v_add_u32_e32 v231, 0x1200, v231
	s_cbranch_scc1 .LBB0_1311
; __device__ __forceinline__ float ex2(float x) { return __builtin_amdgcn_exp2f(x); }
; #define LAS __attribute__((address_space(3)))
; __device__ __forceinline__ s16x4 trr(LAS unsigned char* p) { return __builtin_bit_cast(s16x4, __builtin_amdgcn_ds_read_tr16_b64_v4i16((LAS v4i16_t*)p)); }
; #define MFMA32(a, b, c) __builtin_amdgcn_mfma_f32_32x32x16_bf16((a), (b), (c), 0, 0, 0)
; __device__ __forceinline__ void ssd_stream(const Frame& F, const Args& A, int sidx) {
;     ...
;             {
;                 bf16x8 bfA[8]; f32x4 as4[4], dt4[4]; s16x4 xlo[2], xhi[2];
; #pragma unroll
;                 for (int s = 0; s < 8; ++s) bfA[s] = *(LAS bf16x8*)(BT + (32 * sti + r32) * BS_ + (16 * s + 8 * hh) * 2);
;                 __builtin_amdgcn_sched_barrier(0);
;                 f32x16 Gt;
; #pragma unroll
;                 for (int i = 0; i < 16; ++i) Gt[i] = 0.f;
; #pragma unroll
;                 for (int s = 0; s < 8; ++s) Gt = MFMA32(bfA[s], cf[s], Gt);
; #pragma unroll
;                 for (int s2 = 0; s2 < 2; ++s2) { LAS unsigned char* xa = XT + (32 * sti + 16 * s2 + 4 * hh + qq) * XS_ + (32 * pt + 16 * cb16 + 4 * pp) * 2; xlo[s2] = trr(xa); xhi[s2] = trr(xa + 8 * XS_); }
;                 if (sti < lt) {
;                     const float fl = ex2(acs_l - arr[32 * sti + 31]);
; #pragma unroll
;                     for (int q4 = 0; q4 < 4; ++q4) { as4[q4] = *(LAS f32x4*)(arr + 256 + 32 * sti + 8 * q4 + 4 * hh);
; #pragma unroll
;                         for (int e = 0; e < 4; ++e) Gt[4 * q4 + e] = Gt[4 * q4 + e] * as4[q4][e] * fl; }
;                 } else {
; #pragma unroll
;                     for (int q4 = 0; q4 < 4; ++q4) { const int s0 = 32 * sti + 8 * q4 + 4 * hh; as4[q4] = *(LAS f32x4*)(arr + s0); dt4[q4] = *(LAS f32x4*)(arr + 128 + s0); }
; #pragma unroll
;                     for (int q4 = 0; q4 < 4; ++q4) {
; #pragma unroll
;                         for (int e = 0; e < 4; ++e) { float wv = Gt[4 * q4 + e] * ex2(fminf(acs_l - as4[q4][e], 0.f)) * dt4[q4][e]; if ((8 * q4 + 4 * hh + e) > r32o) wv = 0.f; Gt[4 * q4 + e] = wv; }
;                     }
;                 }
.LBB0_1307:
	v_add_u32_e32 v38, 0, v232
	ds_read_b128 v[186:189], v38 offset:96
	ds_read_b128 v[190:193], v38 offset:128
	ds_read_b128 v[194:197], v38 offset:160
	ds_read_b128 v[198:201], v38 offset:192
	ds_read_b128 v[234:237], v38 offset:224
	s_waitcnt lgkmcnt(7)
	v_mfma_f32_32x32x16_bf16 v[34:49], v[238:241], v[98:101], 0
	s_mov_b64 s[66:67], -1
	s_cmp_lt_i32 s69, s1
	v_add_u32_e32 v233, 0, v230
	s_waitcnt lgkmcnt(6)
	v_mfma_f32_32x32x16_bf16 v[34:49], v[244:247], v[102:105], v[34:49]
	v_add_u32_e32 v132, 0, v231
	s_waitcnt lgkmcnt(5)
	v_mfma_f32_32x32x16_bf16 v[34:49], v[248:251], v[106:109], v[34:49]
	ds_read_b64_tr_b16 v[134:135], v132
	ds_read_b64_tr_b16 v[136:137], v132 offset:1152
	ds_read_b64_tr_b16 v[130:131], v132 offset:2304
	ds_read_b64_tr_b16 v[132:133], v132 offset:3456
	s_waitcnt lgkmcnt(8)
	v_mfma_f32_32x32x16_bf16 v[34:49], v[186:189], v[110:113], v[34:49]
	s_waitcnt lgkmcnt(7)
	v_mfma_f32_32x32x16_bf16 v[34:49], v[190:193], v[114:117], v[34:49]
	s_waitcnt lgkmcnt(6)
	v_mfma_f32_32x32x16_bf16 v[34:49], v[194:197], v[118:121], v[34:49]
	s_waitcnt lgkmcnt(5)
	v_mfma_f32_32x32x16_bf16 v[34:49], v[198:201], v[122:125], v[34:49]
	s_waitcnt lgkmcnt(4)
	v_mfma_f32_32x32x16_bf16 v[34:49], v[234:237], v[126:129], v[34:49]
	s_cbranch_scc1 .LBB0_1309
	v_add_u32_e32 v186, 0x1e400, v233
	v_add_u32_e32 v190, 0x1e600, v233
	ds_read_b128 v[186:189], v186
	ds_read_b128 v[190:193], v190
	v_add_u32_e32 v194, 0x1e420, v233
	v_add_u32_e32 v198, 0x1e620, v233
	ds_read_b128 v[194:197], v194
	ds_read_b128 v[198:201], v198
	s_waitcnt lgkmcnt(3)
	v_sub_f32_e32 v186, v140, v186
	v_sub_f32_e32 v187, v140, v187
	v_sub_f32_e32 v188, v140, v188
	v_sub_f32_e32 v189, v140, v189
	v_min_f32_e32 v186, 0, v186
	v_min_f32_e32 v187, 0, v187
	v_min_f32_e32 v188, 0, v188
	v_min_f32_e32 v189, 0, v189
	v_exp_f32_e32 v186, v186
	v_exp_f32_e32 v187, v187
	v_exp_f32_e32 v188, v188
	v_exp_f32_e32 v189, v189
	v_mul_f32_e32 v186, v34, v186
	v_mul_f32_e32 v187, v35, v187
	s_waitcnt lgkmcnt(2)
	v_mul_f32_e32 v186, v190, v186
	v_pk_mul_f32 v[188:189], v[36:37], v[188:189]
	v_mul_f32_e32 v187, v191, v187
	s_waitcnt lgkmcnt(1)
	v_sub_f32_e32 v190, v140, v194
	v_sub_f32_e32 v191, v140, v195
	v_pk_mul_f32 v[188:189], v[192:193], v[188:189]
	v_sub_f32_e32 v192, v140, v196
	v_sub_f32_e32 v193, v140, v197
	v_min_f32_e32 v190, 0, v190
	v_min_f32_e32 v191, 0, v191
	v_min_f32_e32 v192, 0, v192
	v_min_f32_e32 v193, 0, v193
	v_add_u32_e32 v234, 0x1e440, v233
	v_add_u32_e32 v238, 0x1e640, v233
	v_add_u32_e32 v244, 0x1e460, v233
	v_add_u32_e32 v248, 0x1e660, v233
	v_exp_f32_e32 v190, v190
	v_exp_f32_e32 v191, v191
	v_exp_f32_e32 v192, v192
	v_exp_f32_e32 v193, v193
	ds_read_b128 v[234:237], v234
	ds_read_b128 v[238:241], v238
	ds_read_b128 v[244:247], v244
	ds_read_b128 v[248:251], v248
	v_pk_mul_f32 v[190:191], v[38:39], v[190:191]
	v_pk_mul_f32 v[192:193], v[40:41], v[192:193]
	s_waitcnt lgkmcnt(4)
	v_pk_mul_f32 v[190:191], v[198:199], v[190:191]
	s_waitcnt lgkmcnt(3)
	v_sub_f32_e32 v194, v140, v234
	v_sub_f32_e32 v195, v140, v235
	v_pk_mul_f32 v[192:193], v[200:201], v[192:193]
	v_sub_f32_e32 v196, v140, v236
	v_sub_f32_e32 v197, v140, v237
	s_waitcnt lgkmcnt(1)
	v_sub_f32_e32 v198, v140, v244
	v_sub_f32_e32 v199, v140, v245
	v_sub_f32_e32 v200, v140, v246
	v_sub_f32_e32 v201, v140, v247
	v_min_f32_e32 v194, 0, v194
	v_min_f32_e32 v195, 0, v195
	v_min_f32_e32 v196, 0, v196
	v_min_f32_e32 v197, 0, v197
	v_min_f32_e32 v198, 0, v198
	v_min_f32_e32 v199, 0, v199
	v_min_f32_e32 v200, 0, v200
	v_min_f32_e32 v201, 0, v201
	v_exp_f32_e32 v194, v194
	v_exp_f32_e32 v195, v195
	v_exp_f32_e32 v196, v196
	v_exp_f32_e32 v197, v197
	v_exp_f32_e32 v198, v198
	v_exp_f32_e32 v199, v199
	v_exp_f32_e32 v200, v200
	v_exp_f32_e32 v201, v201
	v_pk_mul_f32 v[194:195], v[42:43], v[194:195]
	v_pk_mul_f32 v[196:197], v[44:45], v[196:197]
	v_pk_mul_f32 v[198:199], v[46:47], v[198:199]
	v_pk_mul_f32 v[200:201], v[48:49], v[200:201]
	v_pk_mul_f32 v[194:195], v[238:239], v[194:195]
	v_pk_mul_f32 v[196:197], v[240:241], v[196:197]
	s_waitcnt lgkmcnt(0)
	v_pk_mul_f32 v[198:199], v[248:249], v[198:199]
	v_pk_mul_f32 v[200:201], v[250:251], v[200:201]
	v_cndmask_b32_e64 v186, v186, 0, s[26:27]
	v_cndmask_b32_e64 v187, 0, v187, s[28:29]
	v_cndmask_b32_e64 v188, v188, 0, s[34:35]
	v_cndmask_b32_e64 v189, v189, 0, s[30:31]
	v_cndmask_b32_e64 v190, v190, 0, s[38:39]
	v_cndmask_b32_e64 v191, v191, 0, s[36:37]
	v_cndmask_b32_e64 v192, v192, 0, s[42:43]
	v_cndmask_b32_e64 v193, v193, 0, s[40:41]
	v_cndmask_b32_e64 v194, v194, 0, s[46:47]
	v_cndmask_b32_e64 v195, v195, 0, s[44:45]
	v_cndmask_b32_e64 v196, v196, 0, s[50:51]
	v_cndmask_b32_e64 v197, v197, 0, s[48:49]
	v_cndmask_b32_e64 v198, v198, 0, s[54:55]
	v_cndmask_b32_e64 v199, v199, 0, s[52:53]
	v_cndmask_b32_e64 v200, v200, 0, s[58:59]
	v_cndmask_b32_e64 v201, v201, 0, s[56:57]
	s_mov_b64 s[66:67], 0
